# long-conv idle-wave weight conversion, software-pipelined across fft32 sections (loads issued one section ahead)
# baseline (speedup 1.0000x reference)
.LBB0_1141:
	s_or_b64 exec, exec, s[4:5]
	s_waitcnt lgkmcnt(0)
	s_barrier
	v_mov_b32_e32 v254, 0
	v_mov_b32_e32 v251, 0

.LBB0_1156:
	s_or_b64 exec, exec, vcc
	v_add_u32_e32 v254, 1, v254
	v_readlane_b32 s100, v255, 6
	s_nop 3
	s_cmp_lt_u32 s100, 4
	s_cbranch_scc1 .Llc_skip_b
	v_readfirstlane_b32 s101, v251
	s_nop 3
	s_cmp_eq_u32 s101, 0
	s_cbranch_scc1 .Llc_nopend_b
	s_waitcnt vmcnt(0)
	v_permlane32_swap_b32_e32 v200, v216
	v_permlane32_swap_b32_e32 v201, v217
	v_permlane32_swap_b32_e32 v202, v218
	v_permlane32_swap_b32_e32 v203, v219
	v_permlane32_swap_b32_e32 v204, v220
	v_permlane32_swap_b32_e32 v205, v221
	v_permlane32_swap_b32_e32 v206, v222
	v_permlane32_swap_b32_e32 v207, v223
	v_permlane32_swap_b32_e32 v208, v224
	v_permlane32_swap_b32_e32 v209, v225
	v_permlane32_swap_b32_e32 v210, v226
	v_permlane32_swap_b32_e32 v211, v227
	v_permlane32_swap_b32_e32 v212, v228
	v_permlane32_swap_b32_e32 v213, v229
	v_permlane32_swap_b32_e32 v214, v230
	v_permlane32_swap_b32_e32 v215, v231
	v_mul_f32_e32 v200, 0x42000000, v200
	v_mul_f32_e32 v201, 0x42000000, v201
	v_mul_f32_e32 v202, 0x42000000, v202
	v_mul_f32_e32 v203, 0x42000000, v203
	v_mul_f32_e32 v204, 0x42000000, v204
	v_mul_f32_e32 v205, 0x42000000, v205
	v_mul_f32_e32 v206, 0x42000000, v206
	v_mul_f32_e32 v207, 0x42000000, v207
	v_mul_f32_e32 v208, 0x42000000, v208
	v_mul_f32_e32 v209, 0x42000000, v209
	v_mul_f32_e32 v210, 0x42000000, v210
	v_mul_f32_e32 v211, 0x42000000, v211
	v_mul_f32_e32 v212, 0x42000000, v212
	v_mul_f32_e32 v213, 0x42000000, v213
	v_mul_f32_e32 v214, 0x42000000, v214
	v_mul_f32_e32 v215, 0x42000000, v215
	v_mul_f32_e32 v216, 0x42000000, v216
	v_mul_f32_e32 v217, 0x42000000, v217
	v_mul_f32_e32 v218, 0x42000000, v218
	v_mul_f32_e32 v219, 0x42000000, v219
	v_mul_f32_e32 v220, 0x42000000, v220
	v_mul_f32_e32 v221, 0x42000000, v221
	v_mul_f32_e32 v222, 0x42000000, v222
	v_mul_f32_e32 v223, 0x42000000, v223
	v_mul_f32_e32 v224, 0x42000000, v224
	v_mul_f32_e32 v225, 0x42000000, v225
	v_mul_f32_e32 v226, 0x42000000, v226
	v_mul_f32_e32 v227, 0x42000000, v227
	v_mul_f32_e32 v228, 0x42000000, v228
	v_mul_f32_e32 v229, 0x42000000, v229
	v_mul_f32_e32 v230, 0x42000000, v230
	v_mul_f32_e32 v231, 0x42000000, v231
	v_cvt_pk_fp8_f32 v232, v200, v216
	v_cvt_pk_fp8_f32 v233, v202, v218
	v_cvt_pk_fp8_f32 v234, v204, v220
	v_cvt_pk_fp8_f32 v235, v206, v222
	v_cvt_pk_fp8_f32 v236, v208, v224
	v_cvt_pk_fp8_f32 v237, v210, v226
	v_cvt_pk_fp8_f32 v238, v212, v228
	v_cvt_pk_fp8_f32 v239, v214, v230
	v_cvt_pk_fp8_f32 v232, v201, v217 op_sel:[0,0,1]
	v_cvt_pk_fp8_f32 v233, v203, v219 op_sel:[0,0,1]
	v_cvt_pk_fp8_f32 v234, v205, v221 op_sel:[0,0,1]
	v_cvt_pk_fp8_f32 v235, v207, v223 op_sel:[0,0,1]
	v_cvt_pk_fp8_f32 v236, v209, v225 op_sel:[0,0,1]
	v_cvt_pk_fp8_f32 v237, v211, v227 op_sel:[0,0,1]
	v_cvt_pk_fp8_f32 v238, v213, v229 op_sel:[0,0,1]
	v_cvt_pk_fp8_f32 v239, v215, v231 op_sel:[0,0,1]
	s_nop 0
	global_store_dwordx4 v241, v[232:235], s[52:53]
	global_store_dwordx4 v241, v[236:239], s[52:53] offset:16
	v_mov_b32_e32 v251, 0
.Llc_nopend_b:
	v_readlane_b32 s100, v255, 6
	s_nop 3
	s_sub_i32 s100, s100, 4
	s_mul_i32 s101, s2, 0x80
	s_add_i32 s100, s100, s101
	v_add_u32_e32 v253, -1, v254
	v_lshl_add_u32 v252, v253, 2, s100
	v_mov_b32_e32 v250, 0x7f00
	v_cmp_lt_u32_e64 s[100:101], v252, v250
	s_nop 3
	s_cmp_eq_u64 s[100:101], 0
	s_cbranch_scc1 .Llc_skip_b
	v_add_u32_e32 v250, 0xc000, v252
	v_add_u32_e32 v249, 0x10100, v252
	v_mov_b32_e32 v236, 0xc00
	v_cmp_gt_u32_e64 s[100:101], v236, v252
	s_nop 1
	v_cndmask_b32_e64 v250, v249, v250, s[100:101]
	v_mov_b32_e32 v249, 0x12000
	v_cmp_ge_u32_e64 s[100:101], v250, v249
	v_mov_b32_e32 v248, 0x3bb00000
	v_mov_b32_e32 v247, 0x3db00000
	v_mov_b32_e32 v246, 0x2b00000
	v_mov_b32_e32 v245, 0x6b00000
	v_cndmask_b32_e64 v248, v248, v246, s[100:101]
	v_cndmask_b32_e64 v247, v247, v245, s[100:101]
	v_mov_b32_e32 v246, 32
	v_cndmask_b32_e64 v246, v246, 48, s[100:101]
	v_mov_b32_e32 v245, 0xc000
	v_cndmask_b32_e64 v245, v245, v249, s[100:101]
	v_sub_u32_e32 v250, v250, v245
	v_mov_b32_e32 v236, 0x4000
	v_cmp_le_u32_e64 s[100:101], v236, v250
	v_subrev_u32_e32 v249, 0x4000, v250
	v_lshrrev_b32_e32 v245, 10, v250
	v_lshrrev_b32_e32 v244, 9, v249
	v_and_b32_e32 v243, 0x3ff, v250
	v_cndmask_b32_e64 v245, v245, v244, s[100:101]
	v_lshrrev_b32_e32 v244, 9, v243
	v_cndmask_b32_e64 v244, v244, 0, s[100:101]
	v_cndmask_b32_e64 v243, v250, v249, s[100:101]
	v_and_b32_e32 v243, 0x1ff, v243
	v_lshrrev_b32_e32 v242, 5, v243
	v_and_b32_e32 v243, 31, v243
	v_mov_b32_e32 v236, 0xc8
	v_lshl_add_u32 v240, v244, 3, v236
	v_mov_b32_e32 v236, 0xd8
	v_cndmask_b32_e64 v240, v240, v236, s[100:101]
	v_lshlrev_b32_e32 v241, 21, v245
	v_add_u32_e32 v241, v241, v248
	v_lshlrev_b32_e32 v239, 20, v245
	v_add_u32_e32 v239, v239, v247
	v_cndmask_b32_e64 v241, v241, v239, s[100:101]
	v_lshrrev_b32_e32 v239, 2, v243
	v_lshlrev_b32_e32 v239, 8, v239
	v_lshl_add_u32 v239, v244, 7, v239
	v_and_b32_e32 v238, 3, v243
	v_lshl_add_u32 v239, v238, 5, v239
	v_lshlrev_b32_e32 v238, 5, v243
	v_cndmask_b32_e64 v239, v239, v238, s[100:101]
	v_and_b32_e32 v238, 63, v0
	v_lshrrev_b32_e32 v237, 5, v238
	v_and_b32_e32 v238, 31, v238
	v_add_u32_e32 v239, v239, v238
	v_lshl_add_u32 v241, v239, 10, v241
	v_lshl_add_u32 v241, v242, 6, v241
	v_lshl_add_u32 v241, v237, 5, v241
	v_add_u32_e32 v246, v246, v245
	v_lshlrev_b32_e32 v246, 22, v246
	v_lshl_add_u32 v239, v242, 6, v237
	v_lshlrev_b32_e32 v239, 10, v239
	v_lshl_add_u32 v239, v243, 5, v239
	v_add_u32_e32 v239, v239, v238
	v_lshl_add_u32 v246, v239, 2, v246
	s_nop 0
	v_readfirstlane_b32 s100, v240
	s_nop 4
	s_load_dwordx2 s[100:101], s[0:1], s100
	s_waitcnt lgkmcnt(0)
	global_load_dword v200, v246, s[100:101]
	v_add_u32_e32 v244, 0x2000, v246
	global_load_dword v201, v244, s[100:101]
	v_add_u32_e32 v245, 0x4000, v246
	global_load_dword v202, v245, s[100:101]
	v_add_u32_e32 v244, 0x6000, v246
	global_load_dword v203, v244, s[100:101]
	v_add_u32_e32 v245, 0x8000, v246
	global_load_dword v204, v245, s[100:101]
	v_add_u32_e32 v244, 0xa000, v246
	global_load_dword v205, v244, s[100:101]
	v_add_u32_e32 v245, 0xc000, v246
	global_load_dword v206, v245, s[100:101]
	v_add_u32_e32 v244, 0xe000, v246
	global_load_dword v207, v244, s[100:101]
	v_add_u32_e32 v245, 0x10000, v246
	global_load_dword v208, v245, s[100:101]
	v_add_u32_e32 v244, 0x12000, v246
	global_load_dword v209, v244, s[100:101]
	v_add_u32_e32 v245, 0x14000, v246
	global_load_dword v210, v245, s[100:101]
	v_add_u32_e32 v244, 0x16000, v246
	global_load_dword v211, v244, s[100:101]
	v_add_u32_e32 v245, 0x18000, v246
	global_load_dword v212, v245, s[100:101]
	v_add_u32_e32 v244, 0x1a000, v246
	global_load_dword v213, v244, s[100:101]
	v_add_u32_e32 v245, 0x1c000, v246
	global_load_dword v214, v245, s[100:101]
	v_add_u32_e32 v244, 0x1e000, v246
	global_load_dword v215, v244, s[100:101]
	v_add_u32_e32 v245, 0x20000, v246
	global_load_dword v216, v245, s[100:101]
	v_add_u32_e32 v244, 0x22000, v246
	global_load_dword v217, v244, s[100:101]
	v_add_u32_e32 v245, 0x24000, v246
	global_load_dword v218, v245, s[100:101]
	v_add_u32_e32 v244, 0x26000, v246
	global_load_dword v219, v244, s[100:101]
	v_add_u32_e32 v245, 0x28000, v246
	global_load_dword v220, v245, s[100:101]
	v_add_u32_e32 v244, 0x2a000, v246
	global_load_dword v221, v244, s[100:101]
	v_add_u32_e32 v245, 0x2c000, v246
	global_load_dword v222, v245, s[100:101]
	v_add_u32_e32 v244, 0x2e000, v246
	global_load_dword v223, v244, s[100:101]
	v_add_u32_e32 v245, 0x30000, v246
	global_load_dword v224, v245, s[100:101]
	v_add_u32_e32 v244, 0x32000, v246
	global_load_dword v225, v244, s[100:101]
	v_add_u32_e32 v245, 0x34000, v246
	global_load_dword v226, v245, s[100:101]
	v_add_u32_e32 v244, 0x36000, v246
	global_load_dword v227, v244, s[100:101]
	v_add_u32_e32 v245, 0x38000, v246
	global_load_dword v228, v245, s[100:101]
	v_add_u32_e32 v244, 0x3a000, v246
	global_load_dword v229, v244, s[100:101]
	v_add_u32_e32 v245, 0x3c000, v246
	global_load_dword v230, v245, s[100:101]
	v_add_u32_e32 v244, 0x3e000, v246
	global_load_dword v231, v244, s[100:101]
	v_mov_b32_e32 v251, 1

.LBB0_1190:
	s_cmp_lt_i32 s61, 18
	s_barrier
	s_cbranch_scc1 .LBB0_1240
	v_readlane_b32 s100, v255, 6
	s_nop 3
	s_cmp_lt_u32 s100, 4
	s_cbranch_scc1 .Llc_skip_f
	v_readfirstlane_b32 s101, v251
	s_nop 3
	s_cmp_eq_u32 s101, 0
	s_cbranch_scc1 .Llc_nopend_f
	s_waitcnt vmcnt(0)
	v_permlane32_swap_b32_e32 v200, v216
	v_permlane32_swap_b32_e32 v201, v217
	v_permlane32_swap_b32_e32 v202, v218
	v_permlane32_swap_b32_e32 v203, v219
	v_permlane32_swap_b32_e32 v204, v220
	v_permlane32_swap_b32_e32 v205, v221
	v_permlane32_swap_b32_e32 v206, v222
	v_permlane32_swap_b32_e32 v207, v223
	v_permlane32_swap_b32_e32 v208, v224
	v_permlane32_swap_b32_e32 v209, v225
	v_permlane32_swap_b32_e32 v210, v226
	v_permlane32_swap_b32_e32 v211, v227
	v_permlane32_swap_b32_e32 v212, v228
	v_permlane32_swap_b32_e32 v213, v229
	v_permlane32_swap_b32_e32 v214, v230
	v_permlane32_swap_b32_e32 v215, v231
	v_mul_f32_e32 v200, 0x42000000, v200
	v_mul_f32_e32 v201, 0x42000000, v201
	v_mul_f32_e32 v202, 0x42000000, v202
	v_mul_f32_e32 v203, 0x42000000, v203
	v_mul_f32_e32 v204, 0x42000000, v204
	v_mul_f32_e32 v205, 0x42000000, v205
	v_mul_f32_e32 v206, 0x42000000, v206
	v_mul_f32_e32 v207, 0x42000000, v207
	v_mul_f32_e32 v208, 0x42000000, v208
	v_mul_f32_e32 v209, 0x42000000, v209
	v_mul_f32_e32 v210, 0x42000000, v210
	v_mul_f32_e32 v211, 0x42000000, v211
	v_mul_f32_e32 v212, 0x42000000, v212
	v_mul_f32_e32 v213, 0x42000000, v213
	v_mul_f32_e32 v214, 0x42000000, v214
	v_mul_f32_e32 v215, 0x42000000, v215
	v_mul_f32_e32 v216, 0x42000000, v216
	v_mul_f32_e32 v217, 0x42000000, v217
	v_mul_f32_e32 v218, 0x42000000, v218
	v_mul_f32_e32 v219, 0x42000000, v219
	v_mul_f32_e32 v220, 0x42000000, v220
	v_mul_f32_e32 v221, 0x42000000, v221
	v_mul_f32_e32 v222, 0x42000000, v222
	v_mul_f32_e32 v223, 0x42000000, v223
	v_mul_f32_e32 v224, 0x42000000, v224
	v_mul_f32_e32 v225, 0x42000000, v225
	v_mul_f32_e32 v226, 0x42000000, v226
	v_mul_f32_e32 v227, 0x42000000, v227
	v_mul_f32_e32 v228, 0x42000000, v228
	v_mul_f32_e32 v229, 0x42000000, v229
	v_mul_f32_e32 v230, 0x42000000, v230
	v_mul_f32_e32 v231, 0x42000000, v231
	v_cvt_pk_fp8_f32 v232, v200, v216
	v_cvt_pk_fp8_f32 v233, v202, v218
	v_cvt_pk_fp8_f32 v234, v204, v220
	v_cvt_pk_fp8_f32 v235, v206, v222
	v_cvt_pk_fp8_f32 v236, v208, v224
	v_cvt_pk_fp8_f32 v237, v210, v226
	v_cvt_pk_fp8_f32 v238, v212, v228
	v_cvt_pk_fp8_f32 v239, v214, v230
	v_cvt_pk_fp8_f32 v232, v201, v217 op_sel:[0,0,1]
	v_cvt_pk_fp8_f32 v233, v203, v219 op_sel:[0,0,1]
	v_cvt_pk_fp8_f32 v234, v205, v221 op_sel:[0,0,1]
	v_cvt_pk_fp8_f32 v235, v207, v223 op_sel:[0,0,1]
	v_cvt_pk_fp8_f32 v236, v209, v225 op_sel:[0,0,1]
	v_cvt_pk_fp8_f32 v237, v211, v227 op_sel:[0,0,1]
	v_cvt_pk_fp8_f32 v238, v213, v229 op_sel:[0,0,1]
	v_cvt_pk_fp8_f32 v239, v215, v231 op_sel:[0,0,1]
	s_nop 0
	global_store_dwordx4 v241, v[232:235], s[52:53]
	global_store_dwordx4 v241, v[236:239], s[52:53] offset:16
	v_mov_b32_e32 v251, 0
.Llc_nopend_f:
.Llc_skip_f:
	s_waitcnt vmcnt(0)
	v_cmp_eq_u32_e32 vcc, 0, v0
	s_barrier
	s_and_saveexec_b64 s[4:5], vcc
	s_cbranch_execz .LBB0_1239
	v_readlane_b32 s3, v255, 10
	s_waitcnt vmcnt(0) expcnt(0) lgkmcnt(0)
	s_nop 0
	v_mov_b32_e32 v1, s3
	ds_read_b32 v3, v1
	ds_read_b32 v1, v1 offset:4
	s_waitcnt lgkmcnt(1)
	v_cmp_ne_u32_e32 vcc, 0, v3
	s_cbranch_vccnz .LBB0_1207
	v_readlane_b32 s6, v255, 0
	v_readlane_b32 s7, v255, 1
	s_load_dwordx2 s[10:11], s[6:7], 0x4
	s_add_u32 s6, s52, 0x4200
	s_addc_u32 s7, s53, 0
	s_add_u32 s8, s52, 0x4400
	s_addc_u32 s9, s53, 0
	s_waitcnt lgkmcnt(0)
	s_mul_i32 s3, s10, s56
	s_add_u32 s10, s52, 0x4500
	s_mul_i32 s3, s3, s11
	s_addc_u32 s11, s53, 0
	s_add_u32 s12, s52, 0x4600
	s_addc_u32 s13, s53, 0
	s_add_u32 s14, s52, 0x4700
	s_addc_u32 s15, s53, 0
	s_add_u32 s16, s52, 0x4800
	s_addc_u32 s17, s53, 0
	s_add_u32 s18, s52, 0x4900
	s_addc_u32 s19, s53, 0
	s_add_u32 s20, s52, 0x4a00
	s_addc_u32 s21, s53, 0
	s_add_u32 s22, s52, 0x4b00
	s_addc_u32 s23, s53, 0
	s_add_u32 s24, s52, 0x4c00
	s_addc_u32 s25, s53, 0
	s_add_u32 s26, s52, 0x4d00
	s_addc_u32 s27, s53, 0
	s_add_u32 s28, s52, 0x4e00
	s_addc_u32 s29, s53, 0
	s_add_u32 s30, s52, 0x4f00
	s_addc_u32 s31, s53, 0
	s_add_u32 s34, s52, 0x5000
	s_addc_u32 s35, s53, 0
	s_add_u32 s36, s52, 0x5100
	s_addc_u32 s37, s53, 0
	s_add_u32 s38, s52, 0x5200
	s_addc_u32 s39, s53, 0
	s_add_u32 s42, s52, 0x5300
	s_addc_u32 s43, s53, 0
	s_mov_b32 s41, 1
	v_mov_b32_e32 v17, 0
	s_branch .LBB0_1195
